# attention merge epilogue: the 128 sub-layer-norm weights staged in LDS once per phase and read from LDS (no global-load wait per unit); static LDS 16896
# speedup vs baseline: 1.0021x; 1.0021x over previous
.LBB0_625:
	s_add_u32 s4, s0, s14
	s_addc_u32 s5, s1, s15
	global_load_dwordx4 v[4:7], v193, s[4:5] offset:48
	global_load_dwordx4 v[8:11], v193, s[4:5] offset:32
	global_load_dwordx4 v[12:15], v193, s[4:5] offset:16
	global_load_dwordx4 v[16:19], v193, s[4:5]
	global_load_dwordx4 v[20:23], v193, s[4:5] offset:304
	global_load_dwordx4 v[24:27], v193, s[4:5] offset:288
	global_load_dwordx4 v[28:31], v193, s[4:5] offset:272
	global_load_dwordx4 v[32:35], v193, s[4:5] offset:256
	global_load_dwordx4 v[36:39], v193, s[4:5] offset:560
	global_load_dwordx4 v[40:43], v193, s[4:5] offset:544
	global_load_dwordx4 v[44:47], v193, s[4:5] offset:528
	global_load_dwordx4 v[48:51], v193, s[4:5] offset:512
	global_load_dwordx4 v[52:55], v193, s[4:5] offset:816
	global_load_dwordx4 v[56:59], v193, s[4:5] offset:800
	global_load_dwordx4 v[60:63], v193, s[4:5] offset:784
	global_load_dwordx4 v[64:67], v193, s[4:5] offset:768
	s_add_u32 s14, s14, 64
	s_addc_u32 s15, s15, 0
	s_cmpk_eq_i32 s14, 0x100
	s_waitcnt vmcnt(12)
	v_mov_b32_e32 v68, v16
	v_mov_b32_e32 v16, v18
	s_waitcnt vmcnt(9)
	v_mov_b32_e32 v18, v28
	s_waitcnt vmcnt(8)
	v_mov_b32_e32 v70, v32
	v_mov_b32_e32 v32, v34
	s_waitcnt vmcnt(4)
	v_mov_b32_e32 v69, v48
	v_mov_b32_e32 v48, v17
	v_mov_b32_e32 v17, v50
	v_mov_b32_e32 v50, v19
	s_waitcnt vmcnt(0)
	v_mov_b32_e32 v71, v64
	v_pk_fma_f32 v[0:1], v[68:69], v[70:71], v[0:1]
	v_mov_b32_e32 v64, v33
	v_pk_fma_f32 v[0:1], v[48:49], v[64:65], v[0:1]
	v_mov_b32_e32 v33, v66
	v_pk_fma_f32 v[0:1], v[16:17], v[32:33], v[0:1]
	v_mov_b32_e32 v66, v35
	v_pk_fma_f32 v[0:1], v[50:51], v[66:67], v[0:1]
	v_mov_b32_e32 v16, v12
	v_mov_b32_e32 v17, v44
	v_mov_b32_e32 v19, v60
	v_pk_fma_f32 v[0:1], v[16:17], v[18:19], v[0:1]
	v_mov_b32_e32 v44, v13
	v_mov_b32_e32 v60, v29
	v_pk_fma_f32 v[0:1], v[44:45], v[60:61], v[0:1]
	v_mov_b32_e32 v12, v14
	v_mov_b32_e32 v13, v46
	v_mov_b32_e32 v16, v30
	v_mov_b32_e32 v17, v62
	v_pk_fma_f32 v[0:1], v[12:13], v[16:17], v[0:1]
	v_mov_b32_e32 v46, v15
	v_mov_b32_e32 v62, v31
	v_pk_fma_f32 v[0:1], v[46:47], v[62:63], v[0:1]
	v_mov_b32_e32 v12, v8
	v_mov_b32_e32 v13, v40
	v_mov_b32_e32 v14, v24
	v_mov_b32_e32 v15, v56
	v_pk_fma_f32 v[0:1], v[12:13], v[14:15], v[0:1]
	v_mov_b32_e32 v40, v9
	v_mov_b32_e32 v56, v25
	v_pk_fma_f32 v[0:1], v[40:41], v[56:57], v[0:1]
	v_mov_b32_e32 v8, v10
	v_mov_b32_e32 v9, v42
	v_mov_b32_e32 v12, v26
	v_mov_b32_e32 v13, v58
	v_pk_fma_f32 v[0:1], v[8:9], v[12:13], v[0:1]
	v_mov_b32_e32 v42, v11
	v_mov_b32_e32 v58, v27
	v_pk_fma_f32 v[0:1], v[42:43], v[58:59], v[0:1]
	v_mov_b32_e32 v8, v4
	v_mov_b32_e32 v9, v36
	v_mov_b32_e32 v10, v20
	v_mov_b32_e32 v11, v52
	v_pk_fma_f32 v[0:1], v[8:9], v[10:11], v[0:1]
	v_mov_b32_e32 v36, v5
	v_mov_b32_e32 v52, v21
	v_pk_fma_f32 v[0:1], v[36:37], v[52:53], v[0:1]
	v_mov_b32_e32 v4, v6
	v_mov_b32_e32 v5, v38
	v_mov_b32_e32 v8, v22
	v_mov_b32_e32 v9, v54
	v_pk_fma_f32 v[0:1], v[4:5], v[8:9], v[0:1]
	v_mov_b32_e32 v38, v7
	v_mov_b32_e32 v54, v23
	v_pk_fma_f32 v[0:1], v[38:39], v[54:55], v[0:1]
	s_cbranch_scc0 .LBB0_625
	v_readfirstlane_b32 s0, v3
	s_cmpk_gt_i32 s0, 0x3ff
	s_cbranch_scc1 .LBB0_654
	v_readlane_b32 s14, v252, 1
	s_mov_b32 s1, 0x3fb8aa3b
	s_mov_b32 s4, 0xc2ce8ed0
	v_cvt_f32_u32_e32 v3, s14
	s_mov_b32 s5, 0x42b17218
	s_add_u32 s6, s6, 0x5720000
	s_addc_u32 s7, s7, 0
	v_mul_f32_e32 v3, 0xbe99999a, v3
	v_mul_f32_e32 v4, 0x3fb8aa3b, v3
	v_fma_f32 v5, v3, s1, -v4
	v_rndne_f32_e32 v6, v4
	v_fmac_f32_e32 v5, 0x32a5705f, v3
	v_sub_f32_e32 v4, v4, v6
	v_add_f32_e32 v4, v4, v5
	v_cvt_i32_f32_e32 v6, v6
	v_exp_f32_e32 v4, v4
	v_cmp_ngt_f32_e32 vcc, s4, v3
	s_add_u32 s10, s10, 0x9b20000
	s_addc_u32 s11, s11, 0
	v_ldexp_f32 v4, v4, v6
	v_cndmask_b32_e32 v4, 0, v4, vcc
	v_cmp_nlt_f32_e32 vcc, s5, v3
	v_readlane_b32 s15, v252, 2
	s_add_u32 s12, s12, 0x3700000
	v_cndmask_b32_e32 v3, v241, v4, vcc
	v_mul_f32_e32 v4, 0x3fb8aa3b, v0
	v_rndne_f32_e32 v5, v4
	v_sub_f32_e32 v6, v4, v5
	v_fma_f32 v4, v0, s1, -v4
	v_fmac_f32_e32 v4, 0x32a5705f, v0
	v_add_f32_e32 v4, v6, v4
	v_exp_f32_e32 v4, v4
	v_cvt_i32_f32_e32 v5, v5
	v_cmp_ngt_f32_e32 vcc, s4, v0
	s_addc_u32 s13, s13, 0
	s_ashr_i32 s28, s2, 8
	v_ldexp_f32 v4, v4, v5
	v_mul_f32_e32 v5, 0x3fb8aa3b, v1
	v_rndne_f32_e32 v6, v5
	v_sub_f32_e32 v7, v5, v6
	v_fma_f32 v5, v1, s1, -v5
	v_fmac_f32_e32 v5, 0x32a5705f, v1
	v_add_f32_e32 v5, v7, v5
	v_exp_f32_e32 v5, v5
	v_cvt_i32_f32_e32 v6, v6
	v_cndmask_b32_e32 v4, 0, v4, vcc
	v_cmp_nlt_f32_e32 vcc, s5, v0
	s_ashr_i32 s16, s2, 6
	v_fmamk_f32 v3, v3, 0xbf19999a, v239
	v_cndmask_b32_e32 v0, v241, v4, vcc
	v_ldexp_f32 v4, v5, v6
	v_cmp_ngt_f32_e32 vcc, s4, v1
	v_sub_f32_e32 v176, 1.0, v3
	v_and_b32_e32 v7, 63, v2
	v_cndmask_b32_e32 v4, 0, v4, vcc
	v_cmp_nlt_f32_e32 vcc, s5, v1
	s_lshl_b64 s[4:5], s[14:15], 9
	s_add_u32 s26, s42, s4
	s_addc_u32 s27, s43, s5
	s_lshl_b32 s1, s0, 1
	s_and_b32 s1, s1, 14
	s_ashr_i32 s4, s0, 7
	s_lshl_b32 s14, s28, 6
	s_lshl_b32 s5, s16, 10
	v_cndmask_b32_e32 v1, v241, v4, vcc
	s_and_b32 s30, s16, 3
	s_add_i32 s1, s1, s4
	s_lshr_b32 s4, s0, 3
	s_ashr_i32 s15, s14, 31
	s_add_i32 s5, s5, 0
	v_sub_f32_e32 v0, v0, v1
	s_cmpk_lt_u32 s2, 0x100
	v_add_f32_e32 v177, v3, v0
	v_lshrrev_b32_e32 v3, 1, v2
	v_lshlrev_b32_e32 v0, 1, v2
	s_cselect_b64 s[16:17], -1, 0
	s_lshl_b32 s2, s28, 13
	v_and_b32_e32 v0, 8, v0
	v_and_b32_e32 v4, 19, v2
	v_and_b32_e32 v6, 4, v3
	s_add_i32 s2, s2, 0
	v_and_b32_e32 v1, 31, v2
	v_or3_b32 v4, v0, v4, v6
	s_cmp_eq_u32 s28, 1
	v_lshl_or_b32 v178, s30, 5, v1
	v_lshl_add_u32 v179, v4, 7, s2
	s_cselect_b64 s[28:29], -1, 0
	v_lshlrev_b32_e32 v1, 7, v1
	s_add_i32 s2, 0, 0x1c000
	v_add_u32_e32 v180, s2, v1
	s_mov_b32 s2, 0xc000
	s_cmp_eq_u32 s30, 1
	s_cselect_b32 s2, 0x8000, s2
	s_cmp_eq_u32 s30, 2
	s_cselect_b32 s2, 0x14000, s2
	s_cmp_eq_u32 s30, 3
	s_cselect_b32 s2, 0x20010, s2
	v_lshrrev_b32_e32 v6, 1, v4
	v_bfe_u32 v8, v2, 5, 1
	s_add_i32 s2, s2, 0
	v_lshl_add_u32 v181, v7, 2, s2
	v_bitop3_b32 v7, v6, v8, 7 bitop3:0x6c
	v_lshlrev_b32_e32 v182, 4, v7
	v_or_b32_e32 v7, 2, v8
	v_bitop3_b32 v7, v6, v7, 7 bitop3:0x6c
	v_lshlrev_b32_e32 v183, 4, v7
	v_or_b32_e32 v7, 4, v8
	v_lshrrev_b32_e32 v9, 4, v2
	v_bitop3_b32 v7, v6, v7, 7 bitop3:0x6c
	v_ashrrev_i32_e32 v160, 3, v2
	v_bfe_u32 v5, v2, 1, 3
	v_xor_b32_e32 v2, v9, v2
	v_lshlrev_b32_e32 v184, 4, v7
	v_or_b32_e32 v7, 6, v8
	v_bitop3_b32 v3, v8, v3, 7 bitop3:0x78
	v_lshlrev_b32_e32 v2, 3, v2
	v_bitop3_b32 v6, v6, v7, 7 bitop3:0x6c
	v_lshlrev_b32_e32 v187, 4, v3
	v_bitop3_b32 v3, v8, v5, 2 bitop3:0x36
	v_lshlrev_b32_e32 v0, 3, v8
	v_and_b32_e32 v2, 56, v2
	v_lshlrev_b32_e32 v4, 2, v8
	v_lshlrev_b32_e32 v192, 4, v8
	v_lshlrev_b32_e32 v185, 4, v6
	v_bitop3_b32 v6, v8, v5, 4 bitop3:0x36
	v_lshlrev_b32_e32 v188, 4, v3
	v_bitop3_b32 v3, v8, v5, 6 bitop3:0x36
	v_ashrrev_i32_e32 v161, 31, v160
	v_lshl_add_u64 v[162:163], s[26:27], 0, v[192:193]
	s_add_i32 s26, s5, 0x10000
	s_add_i32 s27, s5, 0x12000
	s_add_i32 s34, s5, 0x14000
	s_add_i32 s35, s5, 0x16000
	s_add_i32 s36, s5, 0x18000
	s_add_i32 s37, s5, 0x1a000
	s_add_i32 s44, s5, 0x1c000
	s_add_i32 s45, s5, 0x1e000
	v_lshlrev_b32_e32 v186, 4, v6
	v_lshlrev_b32_e32 v189, 4, v3
	v_add_u32_e32 v190, 0, v1
	s_mov_b32 s46, 0
	v_lshlrev_b32_e32 v192, 1, v0
	v_lshlrev_b32_e32 v164, 1, v2
	v_lshlrev_b32_e32 v166, 1, v4
	v_add_u32_e32 v182, v179, v182
	v_add_u32_e32 v183, v179, v183
	v_add_u32_e32 v184, v179, v184
	v_add_u32_e32 v185, v179, v185
	v_add_u32_e32 v187, v190, v187
	v_add_u32_e32 v188, v190, v188
	v_add_u32_e32 v186, v190, v186
	v_add_u32_e32 v189, v190, v189
	v_add_u32_e32 v187, 0x10000, v187
	v_add_u32_e32 v188, 0x10000, v188
	v_add_u32_e32 v186, 0x10000, v186
	v_add_u32_e32 v189, 0x10000, v189
	s_add_u32 s26, s6, 0x800
	s_addc_u32 s27, s7, 0
	s_mov_b32 s35, 0
	v_and_b32_e32 v4, 31, v240
	v_lshlrev_b32_e32 v4, 4, v4
	v_sub_u32_e32 v6, v4, v192
	v_ashrrev_i32_e32 v7, 31, v6
	v_lshl_add_u64 v[6:7], v[162:163], 0, v[6:7]
	global_load_dwordx4 v[0:3], v[6:7], off
	v_add_u32_e32 v4, 0x24010, v4
	s_waitcnt vmcnt(0)
	ds_write_b128 v4, v[0:3]
	s_waitcnt lgkmcnt(0)
	s_mov_b32 s2, s0
	s_branch .LBB0_629

.LBB0_651:
	s_and_b64 vcc, exec, s[38:39]
	s_waitcnt vmcnt(0) lgkmcnt(0)
	s_barrier
	s_cbranch_vccnz .LBB0_628
	v_div_scale_f32 v65, s[38:39], v64, v64, 1.0
	v_rcp_f32_e32 v66, v65
	v_div_scale_f32 v67, vcc, 1.0, v64, 1.0
	s_mov_b32 s31, s3
	v_fma_f32 v68, -v65, v66, 1.0
	v_fmac_f32_e32 v66, v68, v66
	v_mul_f32_e32 v68, v67, v66
	v_fma_f32 v69, -v65, v68, v67
	v_fmac_f32_e32 v68, v69, v66
	v_fma_f32 v65, -v65, v68, v67
	v_div_fmas_f32 v65, v65, v66, v68
	v_div_fixup_f32 v66, v65, v64, 1.0
	ds_read2st64_b32 v[72:73], v181 offset1:1
	ds_read2st64_b32 v[74:75], v181 offset0:2 offset1:3
	ds_read2st64_b32 v[76:77], v181 offset0:4 offset1:5
	ds_read2st64_b32 v[78:79], v181 offset0:6 offset1:7
	ds_read2st64_b32 v[80:81], v181 offset0:8 offset1:9
	ds_read2st64_b32 v[82:83], v181 offset0:10 offset1:11
	ds_read2st64_b32 v[84:85], v181 offset0:12 offset1:13
	ds_read2st64_b32 v[86:87], v181 offset0:14 offset1:15
	ds_read2st64_b32 v[88:89], v181 offset0:16 offset1:17
	ds_read2st64_b32 v[90:91], v181 offset0:18 offset1:19
	ds_read2st64_b32 v[92:93], v181 offset0:20 offset1:21
	ds_read2st64_b32 v[94:95], v181 offset0:22 offset1:23
	ds_read2st64_b32 v[96:97], v181 offset0:24 offset1:25
	ds_read2st64_b32 v[98:99], v181 offset0:26 offset1:27
	ds_read2st64_b32 v[100:101], v181 offset0:28 offset1:29
	ds_read2st64_b32 v[102:103], v181 offset0:30 offset1:31
	ds_read2st64_b32 v[104:105], v181 offset0:32 offset1:33
	ds_read2st64_b32 v[106:107], v181 offset0:34 offset1:35
	ds_read2st64_b32 v[108:109], v181 offset0:36 offset1:37
	ds_read2st64_b32 v[110:111], v181 offset0:38 offset1:39
	ds_read2st64_b32 v[112:113], v181 offset0:40 offset1:41
	ds_read2st64_b32 v[114:115], v181 offset0:42 offset1:43
	ds_read2st64_b32 v[116:117], v181 offset0:44 offset1:45
	ds_read2st64_b32 v[118:119], v181 offset0:46 offset1:47
	ds_read2st64_b32 v[64:65], v181 offset0:58 offset1:59
	ds_read2st64_b32 v[120:121], v181 offset0:48 offset1:49
	ds_read2st64_b32 v[122:123], v181 offset0:50 offset1:51
	ds_read2st64_b32 v[124:125], v181 offset0:52 offset1:53
	ds_read2st64_b32 v[126:127], v181 offset0:54 offset1:55
	ds_read2st64_b32 v[68:69], v181 offset0:60 offset1:61
	ds_read2st64_b32 v[70:71], v181 offset0:62 offset1:63
	ds_read2st64_b32 v[128:129], v181 offset0:56 offset1:57
	s_waitcnt lgkmcnt(0)
	v_fma_f32 v48, v48, v66, -v72
	v_fma_f32 v49, v49, v66, -v73
	v_fma_f32 v50, v50, v66, -v74
	v_fma_f32 v51, v51, v66, -v75
	v_fma_f32 v52, v52, v66, -v76
	v_fma_f32 v53, v53, v66, -v77
	v_fma_f32 v54, v54, v66, -v78
	v_fma_f32 v55, v55, v66, -v79
	v_fma_f32 v56, v56, v66, -v80
	v_fma_f32 v57, v57, v66, -v81
	v_fma_f32 v58, v58, v66, -v82
	v_fma_f32 v59, v59, v66, -v83
	v_fma_f32 v60, v60, v66, -v84
	v_fma_f32 v61, v61, v66, -v85
	v_fma_f32 v62, v62, v66, -v86
	v_fma_f32 v63, v63, v66, -v87
	v_fma_f32 v32, v32, v66, -v88
	v_fma_f32 v33, v33, v66, -v89
	v_fma_f32 v34, v34, v66, -v90
	v_fma_f32 v35, v35, v66, -v91
	v_fma_f32 v36, v36, v66, -v92
	v_fma_f32 v37, v37, v66, -v93
	v_fma_f32 v38, v38, v66, -v94
	v_fma_f32 v39, v39, v66, -v95
	v_fma_f32 v40, v40, v66, -v96
	v_fma_f32 v41, v41, v66, -v97
	v_fma_f32 v42, v42, v66, -v98
	v_fma_f32 v43, v43, v66, -v99
	v_fma_f32 v44, v44, v66, -v100
	v_fma_f32 v45, v45, v66, -v101
	v_fma_f32 v46, v46, v66, -v102
	v_fma_f32 v47, v47, v66, -v103
	v_fma_f32 v16, v16, v66, -v104
	v_fma_f32 v17, v17, v66, -v105
	v_fma_f32 v18, v18, v66, -v106
	v_fma_f32 v19, v19, v66, -v107
	v_fma_f32 v20, v20, v66, -v108
	v_fma_f32 v21, v21, v66, -v109
	v_fma_f32 v22, v22, v66, -v110
	v_fma_f32 v23, v23, v66, -v111
	v_fma_f32 v24, v24, v66, -v112
	v_fma_f32 v25, v25, v66, -v113
	v_fma_f32 v26, v26, v66, -v114
	v_fma_f32 v27, v27, v66, -v115
	v_fma_f32 v28, v28, v66, -v116
	v_fma_f32 v29, v29, v66, -v117
	v_fma_f32 v30, v30, v66, -v118
	v_fma_f32 v31, v31, v66, -v119
	v_fma_f32 v0, v0, v66, -v120
	v_fma_f32 v1, v1, v66, -v121
	v_fma_f32 v2, v2, v66, -v122
	v_fma_f32 v3, v3, v66, -v123
	v_fma_f32 v4, v4, v66, -v124
	v_fma_f32 v5, v5, v66, -v125
	v_fma_f32 v6, v6, v66, -v126
	v_fma_f32 v7, v7, v66, -v127
	v_fma_f32 v8, v8, v66, -v128
	v_fma_f32 v9, v9, v66, -v129
	v_fma_f32 v10, v10, v66, -v64
	v_fma_f32 v11, v11, v66, -v65
	v_fma_f32 v12, v12, v66, -v68
	v_fma_f32 v13, v13, v66, -v69
	v_fma_f32 v14, v14, v66, -v70
	v_fma_f32 v15, v15, v66, -v71
	v_add_u32_e32 v70, 0x24010, v192
	ds_read_b128 v[72:75], v70 offset:0
	ds_read_b128 v[76:79], v70 offset:32
	ds_read_b128 v[80:83], v70 offset:64
	ds_read_b128 v[84:87], v70 offset:96
	ds_read_b128 v[88:91], v70 offset:128
	ds_read_b128 v[92:95], v70 offset:160
	ds_read_b128 v[96:99], v70 offset:192
	ds_read_b128 v[100:103], v70 offset:224
	ds_read_b128 v[104:107], v70 offset:256
	ds_read_b128 v[108:111], v70 offset:288
	ds_read_b128 v[112:115], v70 offset:320
	ds_read_b128 v[116:119], v70 offset:352
	ds_read_b128 v[120:123], v70 offset:384
	ds_read_b128 v[124:127], v70 offset:416
	ds_read_b128 v[128:131], v70 offset:448
	ds_read_b128 v[132:135], v70 offset:480
	v_mul_f32_e32 v64, v48, v48
	v_mul_f32_e32 v65, v49, v49
	v_add_f32_e32 v64, v64, v65
	v_mul_f32_e32 v69, v50, v50
	v_mul_f32_e32 v70, v51, v51
	v_mul_f32_e32 v65, v52, v52
	v_add_f32_e32 v64, v64, v69
	v_mul_f32_e32 v68, v53, v53
	v_add_f32_e32 v64, v64, v70
	v_mul_f32_e32 v69, v54, v54
	v_add_f32_e32 v64, v64, v65
	v_mul_f32_e32 v70, v55, v55
	v_add_f32_e32 v64, v64, v68
	v_mul_f32_e32 v65, v56, v56
	v_add_f32_e32 v64, v64, v69
	v_mul_f32_e32 v68, v57, v57
	v_add_f32_e32 v64, v64, v70
	v_mul_f32_e32 v69, v58, v58
	v_add_f32_e32 v64, v64, v65
	v_mul_f32_e32 v70, v59, v59
	v_add_f32_e32 v64, v64, v68
	v_mul_f32_e32 v65, v60, v60
	v_add_f32_e32 v64, v64, v69
	v_mul_f32_e32 v68, v61, v61
	v_add_f32_e32 v64, v64, v70
	v_mul_f32_e32 v69, v62, v62
	v_add_f32_e32 v64, v64, v65
	v_mul_f32_e32 v70, v63, v63
	v_add_f32_e32 v64, v64, v68
	v_mul_f32_e32 v65, v32, v32
	v_add_f32_e32 v64, v64, v69
	v_mul_f32_e32 v68, v33, v33
	v_add_f32_e32 v64, v64, v70
	v_mul_f32_e32 v69, v34, v34
	v_add_f32_e32 v64, v64, v65
	v_mul_f32_e32 v70, v35, v35
	v_add_f32_e32 v64, v64, v68
	v_mul_f32_e32 v65, v36, v36
	v_add_f32_e32 v64, v64, v69
	v_mul_f32_e32 v68, v37, v37
	v_add_f32_e32 v64, v64, v70
	v_mul_f32_e32 v69, v38, v38
	v_add_f32_e32 v64, v64, v65
	v_mul_f32_e32 v70, v39, v39
	v_add_f32_e32 v64, v64, v68
	v_mul_f32_e32 v65, v40, v40
	v_add_f32_e32 v64, v64, v69
	v_mul_f32_e32 v68, v41, v41
	v_add_f32_e32 v64, v64, v70
	v_mul_f32_e32 v69, v42, v42
	v_add_f32_e32 v64, v64, v65
	v_mul_f32_e32 v70, v43, v43
	v_add_f32_e32 v64, v64, v68
	v_mul_f32_e32 v65, v44, v44
	v_add_f32_e32 v64, v64, v69
	v_mul_f32_e32 v68, v45, v45
	v_add_f32_e32 v64, v64, v70
	v_mul_f32_e32 v69, v46, v46
	v_add_f32_e32 v64, v64, v65
	v_mul_f32_e32 v70, v47, v47
	v_add_f32_e32 v64, v64, v68
	v_mul_f32_e32 v65, v16, v16
	v_add_f32_e32 v64, v64, v69
	v_mul_f32_e32 v68, v17, v17
	v_add_f32_e32 v64, v64, v70
	v_mul_f32_e32 v69, v18, v18
	v_add_f32_e32 v64, v64, v65
	v_mul_f32_e32 v70, v19, v19
	v_add_f32_e32 v64, v64, v68
	v_mul_f32_e32 v65, v20, v20
	v_add_f32_e32 v64, v64, v69
	v_mul_f32_e32 v68, v21, v21
	v_add_f32_e32 v64, v64, v70
	v_mul_f32_e32 v69, v22, v22
	v_add_f32_e32 v64, v64, v65
	v_mul_f32_e32 v70, v23, v23
	v_add_f32_e32 v64, v64, v68
	v_mul_f32_e32 v65, v24, v24
	v_add_f32_e32 v64, v64, v69
	v_mul_f32_e32 v68, v25, v25
	v_add_f32_e32 v64, v64, v70
	v_mul_f32_e32 v69, v26, v26
	v_add_f32_e32 v64, v64, v65
	v_mul_f32_e32 v70, v27, v27
	v_add_f32_e32 v64, v64, v68
	v_mul_f32_e32 v65, v28, v28
	v_add_f32_e32 v64, v64, v69
	v_mul_f32_e32 v68, v29, v29
	v_add_f32_e32 v64, v64, v70
	v_mul_f32_e32 v69, v30, v30
	v_add_f32_e32 v64, v64, v65
	v_mul_f32_e32 v70, v31, v31
	v_add_f32_e32 v64, v64, v68
	v_mul_f32_e32 v65, v0, v0
	v_add_f32_e32 v64, v64, v69
	v_mul_f32_e32 v68, v1, v1
	v_add_f32_e32 v64, v64, v70
	v_mul_f32_e32 v69, v2, v2
	v_add_f32_e32 v64, v64, v65
	v_mul_f32_e32 v70, v3, v3
	v_add_f32_e32 v64, v64, v68
	v_mul_f32_e32 v65, v4, v4
	v_add_f32_e32 v64, v64, v69
	v_mul_f32_e32 v68, v5, v5
	v_add_f32_e32 v64, v64, v70
	v_mul_f32_e32 v69, v6, v6
	v_add_f32_e32 v64, v64, v65
	v_mul_f32_e32 v70, v7, v7
	v_add_f32_e32 v64, v64, v68
	v_mul_f32_e32 v65, v8, v8
	v_add_f32_e32 v64, v64, v69
	v_mul_f32_e32 v68, v9, v9
	v_add_f32_e32 v64, v64, v70
	v_mul_f32_e32 v69, v10, v10
	v_add_f32_e32 v64, v64, v65
	v_mul_f32_e32 v70, v11, v11
	v_add_f32_e32 v64, v64, v68
	v_mul_f32_e32 v65, v12, v12
	v_add_f32_e32 v64, v64, v69
	v_mul_f32_e32 v68, v13, v13
	v_add_f32_e32 v64, v64, v70
	v_mul_f32_e32 v69, v14, v14
	v_add_f32_e32 v64, v64, v65
	v_mul_f32_e32 v70, v15, v15
	v_add_f32_e32 v64, v64, v68
	v_add_f32_e32 v64, v64, v69
	v_add_f32_e32 v64, v64, v70
	ds_bpermute_b32 v65, v165, v64
	v_lshlrev_b64 v[68:69], 11, v[168:169]
	v_lshl_add_u64 v[68:69], s[12:13], 0, v[68:69]
	v_lshl_add_u64 v[68:69], v[68:69], 0, s[30:31]
	v_mov_b32_e32 v167, v193
	s_waitcnt lgkmcnt(0)
	v_add_f32_e32 v64, v64, v65
	v_fmamk_f32 v64, v64, 0x3c000000, v238
	v_rsq_f32_e32 v64, v64
	v_lshl_add_u64 v[68:69], v[68:69], 0, v[166:167]
	v_mul_f32_e32 v70, v176, v64
	v_mul_f32_e32 v48, v48, v70
	v_mul_f32_e32 v49, v49, v70
	v_mul_f32_e32 v50, v50, v70
	v_mul_f32_e32 v51, v51, v70
	v_mul_f32_e32 v72, v72, v48
	v_mul_f32_e32 v73, v73, v49
	v_mul_f32_e32 v74, v74, v50
	v_mul_f32_e32 v75, v75, v51
	v_cvt_pk_bf16_f32 v72, v72, v73
	v_cvt_pk_bf16_f32 v73, v74, v75
	global_store_dwordx2 v[68:69], v[72:73], off offset:0
	v_mul_f32_e32 v52, v52, v70
	v_mul_f32_e32 v53, v53, v70
	v_mul_f32_e32 v54, v54, v70
	v_mul_f32_e32 v55, v55, v70
	v_mul_f32_e32 v76, v76, v52
	v_mul_f32_e32 v77, v77, v53
	v_mul_f32_e32 v78, v78, v54
	v_mul_f32_e32 v79, v79, v55
	v_cvt_pk_bf16_f32 v76, v76, v77
	v_cvt_pk_bf16_f32 v77, v78, v79
	global_store_dwordx2 v[68:69], v[76:77], off offset:16
	v_mul_f32_e32 v56, v56, v70
	v_mul_f32_e32 v57, v57, v70
	v_mul_f32_e32 v58, v58, v70
	v_mul_f32_e32 v59, v59, v70
	v_mul_f32_e32 v80, v80, v56
	v_mul_f32_e32 v81, v81, v57
	v_mul_f32_e32 v82, v82, v58
	v_mul_f32_e32 v83, v83, v59
	v_cvt_pk_bf16_f32 v80, v80, v81
	v_cvt_pk_bf16_f32 v81, v82, v83
	global_store_dwordx2 v[68:69], v[80:81], off offset:32
	v_mul_f32_e32 v60, v60, v70
	v_mul_f32_e32 v61, v61, v70
	v_mul_f32_e32 v62, v62, v70
	v_mul_f32_e32 v63, v63, v70
	v_mul_f32_e32 v84, v84, v60
	v_mul_f32_e32 v85, v85, v61
	v_mul_f32_e32 v86, v86, v62
	v_mul_f32_e32 v87, v87, v63
	v_cvt_pk_bf16_f32 v84, v84, v85
	v_cvt_pk_bf16_f32 v85, v86, v87
	global_store_dwordx2 v[68:69], v[84:85], off offset:48
	v_mul_f32_e32 v32, v32, v70
	v_mul_f32_e32 v33, v33, v70
	v_mul_f32_e32 v34, v34, v70
	v_mul_f32_e32 v35, v35, v70
	v_mul_f32_e32 v88, v88, v32
	v_mul_f32_e32 v89, v89, v33
	v_mul_f32_e32 v90, v90, v34
	v_mul_f32_e32 v91, v91, v35
	v_cvt_pk_bf16_f32 v88, v88, v89
	v_cvt_pk_bf16_f32 v89, v90, v91
	global_store_dwordx2 v[68:69], v[88:89], off offset:64
	v_mul_f32_e32 v36, v36, v70
	v_mul_f32_e32 v37, v37, v70
	v_mul_f32_e32 v38, v38, v70
	v_mul_f32_e32 v39, v39, v70
	v_mul_f32_e32 v92, v92, v36
	v_mul_f32_e32 v93, v93, v37
	v_mul_f32_e32 v94, v94, v38
	v_mul_f32_e32 v95, v95, v39
	v_cvt_pk_bf16_f32 v92, v92, v93
	v_cvt_pk_bf16_f32 v93, v94, v95
	global_store_dwordx2 v[68:69], v[92:93], off offset:80
	v_mul_f32_e32 v40, v40, v70
	v_mul_f32_e32 v41, v41, v70
	v_mul_f32_e32 v42, v42, v70
	v_mul_f32_e32 v43, v43, v70
	v_mul_f32_e32 v96, v96, v40
	v_mul_f32_e32 v97, v97, v41
	v_mul_f32_e32 v98, v98, v42
	v_mul_f32_e32 v99, v99, v43
	v_cvt_pk_bf16_f32 v96, v96, v97
	v_cvt_pk_bf16_f32 v97, v98, v99
	global_store_dwordx2 v[68:69], v[96:97], off offset:96
	v_mul_f32_e32 v44, v44, v70
	v_mul_f32_e32 v45, v45, v70
	v_mul_f32_e32 v46, v46, v70
	v_mul_f32_e32 v47, v47, v70
	v_mul_f32_e32 v100, v100, v44
	v_mul_f32_e32 v101, v101, v45
	v_mul_f32_e32 v102, v102, v46
	v_mul_f32_e32 v103, v103, v47
	v_cvt_pk_bf16_f32 v100, v100, v101
	v_cvt_pk_bf16_f32 v101, v102, v103
	global_store_dwordx2 v[68:69], v[100:101], off offset:112
	v_mul_f32_e32 v16, v16, v70
	v_mul_f32_e32 v17, v17, v70
	v_mul_f32_e32 v18, v18, v70
	v_mul_f32_e32 v19, v19, v70
	v_mul_f32_e32 v104, v104, v16
	v_mul_f32_e32 v105, v105, v17
	v_mul_f32_e32 v106, v106, v18
	v_mul_f32_e32 v107, v107, v19
	v_cvt_pk_bf16_f32 v104, v104, v105
	v_cvt_pk_bf16_f32 v105, v106, v107
	global_store_dwordx2 v[68:69], v[104:105], off offset:128
	v_mul_f32_e32 v20, v20, v70
	v_mul_f32_e32 v21, v21, v70
	v_mul_f32_e32 v22, v22, v70
	v_mul_f32_e32 v23, v23, v70
	v_mul_f32_e32 v108, v108, v20
	v_mul_f32_e32 v109, v109, v21
	v_mul_f32_e32 v110, v110, v22
	v_mul_f32_e32 v111, v111, v23
	v_cvt_pk_bf16_f32 v108, v108, v109
	v_cvt_pk_bf16_f32 v109, v110, v111
	global_store_dwordx2 v[68:69], v[108:109], off offset:144
	v_mul_f32_e32 v24, v24, v70
	v_mul_f32_e32 v25, v25, v70
	v_mul_f32_e32 v26, v26, v70
	v_mul_f32_e32 v27, v27, v70
	v_mul_f32_e32 v112, v112, v24
	v_mul_f32_e32 v113, v113, v25
	v_mul_f32_e32 v114, v114, v26
	v_mul_f32_e32 v115, v115, v27
	v_cvt_pk_bf16_f32 v112, v112, v113
	v_cvt_pk_bf16_f32 v113, v114, v115
	global_store_dwordx2 v[68:69], v[112:113], off offset:160
	v_mul_f32_e32 v28, v28, v70
	v_mul_f32_e32 v29, v29, v70
	v_mul_f32_e32 v30, v30, v70
	v_mul_f32_e32 v31, v31, v70
	v_mul_f32_e32 v116, v116, v28
	v_mul_f32_e32 v117, v117, v29
	v_mul_f32_e32 v118, v118, v30
	v_mul_f32_e32 v119, v119, v31
	v_cvt_pk_bf16_f32 v116, v116, v117
	v_cvt_pk_bf16_f32 v117, v118, v119
	global_store_dwordx2 v[68:69], v[116:117], off offset:176
	v_mul_f32_e32 v0, v0, v70
	v_mul_f32_e32 v1, v1, v70
	v_mul_f32_e32 v2, v2, v70
	v_mul_f32_e32 v3, v3, v70
	v_mul_f32_e32 v120, v120, v0
	v_mul_f32_e32 v121, v121, v1
	v_mul_f32_e32 v122, v122, v2
	v_mul_f32_e32 v123, v123, v3
	v_cvt_pk_bf16_f32 v120, v120, v121
	v_cvt_pk_bf16_f32 v121, v122, v123
	global_store_dwordx2 v[68:69], v[120:121], off offset:192
	v_mul_f32_e32 v4, v4, v70
	v_mul_f32_e32 v5, v5, v70
	v_mul_f32_e32 v6, v6, v70
	v_mul_f32_e32 v7, v7, v70
	v_mul_f32_e32 v124, v124, v4
	v_mul_f32_e32 v125, v125, v5
	v_mul_f32_e32 v126, v126, v6
	v_mul_f32_e32 v127, v127, v7
	v_cvt_pk_bf16_f32 v124, v124, v125
	v_cvt_pk_bf16_f32 v125, v126, v127
	global_store_dwordx2 v[68:69], v[124:125], off offset:208
	v_mul_f32_e32 v8, v8, v70
	v_mul_f32_e32 v9, v9, v70
	v_mul_f32_e32 v10, v10, v70
	v_mul_f32_e32 v11, v11, v70
	v_mul_f32_e32 v128, v128, v8
	v_mul_f32_e32 v129, v129, v9
	v_mul_f32_e32 v130, v130, v10
	v_mul_f32_e32 v131, v131, v11
	v_cvt_pk_bf16_f32 v128, v128, v129
	v_cvt_pk_bf16_f32 v129, v130, v131
	global_store_dwordx2 v[68:69], v[128:129], off offset:224
	v_mul_f32_e32 v12, v12, v70
	v_mul_f32_e32 v13, v13, v70
	v_mul_f32_e32 v14, v14, v70
	v_mul_f32_e32 v15, v15, v70
	v_mul_f32_e32 v132, v132, v12
	v_mul_f32_e32 v133, v133, v13
	v_mul_f32_e32 v134, v134, v14
	v_mul_f32_e32 v135, v135, v15
	v_cvt_pk_bf16_f32 v132, v132, v133
	v_cvt_pk_bf16_f32 v133, v134, v135
	global_store_dwordx2 v[68:69], v[132:133], off offset:240
	s_branch .LBB0_628

	.amdhsa_kernel _Z14fwd_megakernelILb1EEv6Params
		.amdhsa_group_segment_fixed_size 16896
		.amdhsa_private_segment_fixed_size 0
		.amdhsa_kernarg_size 384
		.amdhsa_user_sgpr_count 2
		.amdhsa_user_sgpr_dispatch_ptr 0
		.amdhsa_user_sgpr_queue_ptr 0
		.amdhsa_user_sgpr_kernarg_segment_ptr 1
		.amdhsa_user_sgpr_dispatch_id 0
		.amdhsa_user_sgpr_kernarg_preload_length 0
		.amdhsa_user_sgpr_kernarg_preload_offset 0
		.amdhsa_user_sgpr_private_segment_size 0
		.amdhsa_uses_dynamic_stack 0
		.amdhsa_enable_private_segment 0
		.amdhsa_system_sgpr_workgroup_id_x 1
		.amdhsa_system_sgpr_workgroup_id_y 0
		.amdhsa_system_sgpr_workgroup_id_z 0
		.amdhsa_system_sgpr_workgroup_info 0
		.amdhsa_system_vgpr_workitem_id 2
		.amdhsa_next_free_vgpr 256
		.amdhsa_next_free_sgpr 100
		.amdhsa_accum_offset 256
		.amdhsa_reserve_vcc 1
		.amdhsa_float_round_mode_32 0
		.amdhsa_float_round_mode_16_64 0
		.amdhsa_float_denorm_mode_32 3
		.amdhsa_float_denorm_mode_16_64 3
		.amdhsa_dx10_clamp 1
		.amdhsa_ieee_mode 1
		.amdhsa_fp16_overflow 0
		.amdhsa_tg_split 0
		.amdhsa_exception_fp_ieee_invalid_op 0
		.amdhsa_exception_fp_denorm_src 0
		.amdhsa_exception_fp_ieee_div_zero 0
		.amdhsa_exception_fp_ieee_overflow 0
		.amdhsa_exception_fp_ieee_underflow 0
		.amdhsa_exception_fp_ieee_inexact 0
		.amdhsa_exception_int_div_zero 0
	.end_amdhsa_kernel

amdhsa.kernels:
  - .agpr_count:     0
    .args:
      - .offset:         0
        .size:           128
        .value_kind:     by_value
      - .offset:         128
        .size:           4
        .value_kind:     hidden_block_count_x
      - .offset:         132
        .size:           4
        .value_kind:     hidden_block_count_y
      - .offset:         136
        .size:           4
        .value_kind:     hidden_block_count_z
      - .offset:         140
        .size:           2
        .value_kind:     hidden_group_size_x
      - .offset:         142
        .size:           2
        .value_kind:     hidden_group_size_y
      - .offset:         144
        .size:           2
        .value_kind:     hidden_group_size_z
      - .offset:         146
        .size:           2
        .value_kind:     hidden_remainder_x
      - .offset:         148
        .size:           2
        .value_kind:     hidden_remainder_y
      - .offset:         150
        .size:           2
        .value_kind:     hidden_remainder_z
      - .offset:         168
        .size:           8
        .value_kind:     hidden_global_offset_x
      - .offset:         176
        .size:           8
        .value_kind:     hidden_global_offset_y
      - .offset:         184
        .size:           8
        .value_kind:     hidden_global_offset_z
      - .offset:         192
        .size:           2
        .value_kind:     hidden_grid_dims
      - .offset:         216
        .size:           8
        .value_kind:     hidden_multigrid_sync_arg
      - .offset:         248
        .size:           4
        .value_kind:     hidden_dynamic_lds_size
    .group_segment_fixed_size: 16896
    .kernarg_segment_align: 8
    .kernarg_segment_size: 384
    .language:       OpenCL C
    .language_version:
      - 2
      - 0
    .max_flat_workgroup_size: 512
    .name:           _Z14fwd_megakernelILb1EEv6Params
    .private_segment_fixed_size: 0
    .sgpr_count:     106
    .sgpr_spill_count: 87
    .symbol:         _Z14fwd_megakernelILb1EEv6Params.kd
    .uniform_work_group_size: 1
    .uses_dynamic_stack: false
    .vgpr_count:     256
    .vgpr_spill_count: 0
    .wavefront_size: 64
  - .agpr_count:     0
    .args:
      - .offset:         0
        .size:           128
        .value_kind:     by_value
      - .offset:         128
        .size:           4
        .value_kind:     hidden_block_count_x
      - .offset:         132
        .size:           4
        .value_kind:     hidden_block_count_y
      - .offset:         136
        .size:           4
        .value_kind:     hidden_block_count_z
      - .offset:         140
        .size:           2
        .value_kind:     hidden_group_size_x
      - .offset:         142
        .size:           2
        .value_kind:     hidden_group_size_y
      - .offset:         144
        .size:           2
        .value_kind:     hidden_group_size_z
      - .offset:         146
        .size:           2
        .value_kind:     hidden_remainder_x
      - .offset:         148
        .size:           2
        .value_kind:     hidden_remainder_y
      - .offset:         150
        .size:           2
        .value_kind:     hidden_remainder_z
      - .offset:         168
        .size:           8
        .value_kind:     hidden_global_offset_x
      - .offset:         176
        .size:           8
        .value_kind:     hidden_global_offset_y
      - .offset:         184
        .size:           8
        .value_kind:     hidden_global_offset_z
      - .offset:         192
        .size:           2
        .value_kind:     hidden_grid_dims
      - .offset:         216
        .size:           8
        .value_kind:     hidden_multigrid_sync_arg
      - .offset:         248
        .size:           4
        .value_kind:     hidden_dynamic_lds_size
    .group_segment_fixed_size: 0
    .kernarg_segment_align: 8
    .kernarg_segment_size: 384
    .language:       OpenCL C
    .language_version:
      - 2
      - 0
    .max_flat_workgroup_size: 512
    .name:           _Z14fwd_megakernelILb0EEv6Params
    .private_segment_fixed_size: 0
    .sgpr_count:     106
    .sgpr_spill_count: 88
    .symbol:         _Z14fwd_megakernelILb0EEv6Params.kd
    .uniform_work_group_size: 1
    .uses_dynamic_stack: false
    .vgpr_count:     246
    .vgpr_spill_count: 0
    .wavefront_size: 64
